# comb18 + counted LDS waits at first consumer in the attention QK^T blocks (lgkmcnt(1)/(2) instead of full drains)
# speedup vs baseline: 1.0067x; 1.0030x over previous
; #define LAS __attribute__((address_space(3)))
; __device__ __forceinline__ unsigned cvt_pk(float lo, float hi) { unsigned r; asm volatile("v_cvt_pk_bf16_f32 %0, %1, %2" : "=v"(r) : "v"(lo), "v"(hi)); return r; }
; __device__ __forceinline__ void attn_unit(LAS unsigned char* lds, int b, int h, int q0, int kbeg, int ntiles, const bf16_t* Q, const bf16_t* K, const bf16_t* Vt, bf16_t* cat) {
;     ...
;         const LAS unsigned char* kb = lds + (buf ^ 1) * AK_BYTES + r32 * (KP * 2) + hi * 16;
;         f32x16 pn0, pn1;
; #pragma unroll
;         for (int r = 0; r < 16; ++r) { pn0[r] = 0.f; pn1[r] = 0.f; }
;         float ps = 0.f; u32x4 pw[4];
;         bf16x8 ka = *(const LAS bf16x8*)(kb), kbb = *(const LAS bf16x8*)(kb + 32 * (KP * 2));
; #pragma unroll
;         for (int ds = 0; ds < 12; ++ds) {
;             bf16x8 na = ka, nb = kbb;
;             if (ds < 11) { na = *(const LAS bf16x8*)(kb + (ds + 1) * 32); nb = *(const LAS bf16x8*)(kb + 32 * (KP * 2) + (ds + 1) * 32); }
;             pn0 = __builtin_amdgcn_mfma_f32_32x32x16_bf16(ka, qf[ds], pn0, 0, 0, 0);
;             pn1 = __builtin_amdgcn_mfma_f32_32x32x16_bf16(kbb, qf[ds], pn1, 0, 0, 0);
;             if (ds < 8) {
;                 float e[4];
; #pragma unroll
;                 for (int j = 0; j < 4; ++j) { const float v = ds < 4 ? pc0[4 * ds + j] : pc1[4 * (ds - 4) + j]; e[j] = __builtin_amdgcn_exp2f(v - mrun); }
;                 ps += (e[0] + e[1]) + (e[2] + e[3]);
;                 const unsigned w0 = cvt_pk(e[0], e[1]), w1 = cvt_pk(e[2], e[3]);
;                 if ((ds & 1) == 0) { pw[ds >> 1].x = w0; pw[ds >> 1].y = w1; } else { pw[ds >> 1].z = w0; pw[ds >> 1].w = w1; }
;             }
;             ka = na; kbb = nb;
;             __builtin_amdgcn_sched_barrier(0);
;         }
.LBB0_814:
	s_xor_b32 s6, s5, 1
	s_mul_i32 s7, s6, 0x6400
	v_add_u32_e32 v236, s7, v228
	ds_read_b128 v[98:101], v236
	v_sub_f32_e32 v82, v82, v230
	v_exp_f32_e32 v197, v82
	v_sub_f32_e32 v82, v84, v230
	v_exp_f32_e32 v201, v82
	v_sub_f32_e32 v82, v85, v230
	v_exp_f32_e32 v233, v82
	v_sub_f32_e32 v82, v86, v230
	v_exp_f32_e32 v196, v82
	v_sub_f32_e32 v82, v87, v230
	s_waitcnt lgkmcnt(0)
	v_mfma_f32_32x32x16_bf16 v[98:113], v[98:101], v[174:177], 0
	v_exp_f32_e32 v198, v82
	v_sub_f32_e32 v82, v88, v230
	v_sub_f32_e32 v83, v83, v230
	v_exp_f32_e32 v200, v82
	v_sub_f32_e32 v82, v89, v230
	v_exp_f32_e32 v199, v83
	v_exp_f32_e32 v232, v82
	ds_read_b128 v[188:191], v236 offset:32
	ds_read_b128 v[114:117], v236 offset:12800
	ds_read_b128 v[192:195], v236 offset:12832
	s_add_i32 s4, s4, 1
	v_add_f32_e32 v82, v196, v198
	v_add_f32_e32 v83, v197, v199
	v_add_f32_e32 v84, v200, v232
	v_add_f32_e32 v85, v201, v233
	s_waitcnt lgkmcnt(1)
	v_mfma_f32_32x32x16_bf16 v[114:129], v[114:117], v[174:177], 0
	v_add_f32_e64 v234, v82, v84
	v_add_f32_e64 v235, v83, v85
	v_cvt_pk_bf16_f32 v186, v197, v199
	v_cvt_pk_bf16_f32 v187, v201, v233
	v_add_f32_e32 v235, 0, v235
	v_mfma_f32_32x32x16_bf16 v[98:113], v[188:191], v[170:173], v[98:113]
	ds_read_b128 v[82:85], v236 offset:64
	ds_read_b128 v[86:89], v236 offset:12864
	v_add_f32_e32 v197, v234, v235
	v_cvt_pk_bf16_f32 v188, v196, v198
	v_cvt_pk_bf16_f32 v189, v200, v232
	s_waitcnt lgkmcnt(2)
	v_mfma_f32_32x32x16_bf16 v[114:129], v[192:195], v[170:173], v[114:129]
	v_sub_f32_e32 v90, v90, v230
	s_waitcnt lgkmcnt(1)
	v_mfma_f32_32x32x16_bf16 v[98:113], v[82:85], v[166:169], v[98:113]
	v_exp_f32_e32 v190, v90
	v_sub_f32_e32 v90, v91, v230
	v_exp_f32_e32 v192, v90
	v_sub_f32_e32 v90, v92, v230
	v_sub_f32_e32 v82, v93, v230
	v_exp_f32_e32 v191, v90
	v_exp_f32_e32 v193, v82
	ds_read_b128 v[82:85], v236 offset:96
	ds_read_b128 v[90:93], v236 offset:12896
	s_waitcnt lgkmcnt(2)
	v_mfma_f32_32x32x16_bf16 v[114:129], v[86:89], v[166:169], v[114:129]
	v_add_f32_e64 v194, v190, v192
	v_add_f32_e64 v195, v191, v193
	v_add_f32_e64 v198, v194, v194
	v_add_f32_e64 v199, v194, v195
	v_cvt_pk_bf16_f32 v190, v190, v192
	v_cvt_pk_bf16_f32 v191, v191, v193
	v_sub_f32_e32 v86, v94, v230
	s_waitcnt lgkmcnt(1)
	v_mfma_f32_32x32x16_bf16 v[98:113], v[82:85], v[162:165], v[98:113]
	v_exp_f32_e32 v94, v86
	v_sub_f32_e32 v86, v95, v230
	v_exp_f32_e32 v192, v86
	v_sub_f32_e32 v86, v96, v230
	v_sub_f32_e32 v82, v97, v230
	v_exp_f32_e32 v96, v86
	v_exp_f32_e32 v193, v82
	ds_read_b128 v[82:85], v236 offset:128
	ds_read_b128 v[86:89], v236 offset:12928
	v_add_f32_e32 v95, v94, v192
	v_cvt_pk_bf16_f32 v192, v94, v192
	v_add_f32_e32 v97, v96, v193
	s_waitcnt lgkmcnt(2)
	v_mfma_f32_32x32x16_bf16 v[114:129], v[90:93], v[162:165], v[114:129]
	v_cvt_pk_bf16_f32 v193, v96, v193
	v_sub_f32_e32 v66, v66, v230
	v_exp_f32_e32 v94, v66
	v_sub_f32_e32 v66, v67, v230
	v_exp_f32_e32 v96, v66
	v_sub_f32_e32 v66, v68, v230
	v_exp_f32_e32 v198, v66
	s_waitcnt lgkmcnt(1)
	v_mfma_f32_32x32x16_bf16 v[98:113], v[82:85], v[158:161], v[98:113]
	v_sub_f32_e32 v66, v69, v230
	v_exp_f32_e32 v196, v66
	ds_read_b128 v[66:69], v236 offset:160
	ds_read_b128 v[82:85], v236 offset:12960
	v_add_f32_e32 v90, v94, v96
	v_add_f32_e32 v91, v95, v97
	v_cvt_pk_bf16_f32 v194, v94, v96
	v_add_f32_e32 v92, v198, v196
	v_add_f32_e32 v93, v199, v197
	v_cvt_pk_bf16_f32 v195, v198, v196
	s_waitcnt lgkmcnt(2)
	v_mfma_f32_32x32x16_bf16 v[114:129], v[86:89], v[158:161], v[114:129]
	v_add_f32_e64 v90, v90, v92
	v_add_f32_e64 v91, v91, v93
	v_add_f32_e64 v86, v90, v90
	v_add_f32_e64 v87, v90, v91
	v_sub_f32_e32 v70, v70, v230
	v_exp_f32_e32 v88, v70
	v_sub_f32_e32 v70, v71, v230
	s_waitcnt lgkmcnt(1)
	v_mfma_f32_32x32x16_bf16 v[98:113], v[66:69], v[154:157], v[98:113]
	v_exp_f32_e32 v90, v70
	v_sub_f32_e32 v70, v72, v230
	v_sub_f32_e32 v66, v73, v230
	v_exp_f32_e32 v89, v70
	v_exp_f32_e32 v91, v66
	ds_read_b128 v[66:69], v236 offset:192
	ds_read_b128 v[70:73], v236 offset:12992
	v_cvt_pk_bf16_f32 v196, v88, v90
	s_waitcnt lgkmcnt(2)
	v_mfma_f32_32x32x16_bf16 v[114:129], v[82:85], v[154:157], v[114:129]
	v_add_f32_e64 v92, v88, v90
	v_add_f32_e64 v93, v89, v91
	v_cvt_pk_bf16_f32 v197, v89, v91
	v_add_f32_e32 v93, v92, v93
	v_add_f32_e32 v92, v92, v92
	v_sub_f32_e32 v74, v74, v230
	s_waitcnt lgkmcnt(1)
	v_mfma_f32_32x32x16_bf16 v[98:113], v[66:69], v[150:153], v[98:113]
	v_exp_f32_e32 v82, v74
	v_sub_f32_e32 v74, v75, v230
	v_exp_f32_e32 v84, v74
	v_sub_f32_e32 v74, v76, v230
	v_sub_f32_e32 v66, v77, v230
	v_exp_f32_e32 v86, v74
	v_exp_f32_e32 v88, v66
	ds_read_b128 v[66:69], v236 offset:224
	ds_read_b128 v[74:77], v236 offset:13024
	v_add_f32_e32 v83, v82, v84
	v_cvt_pk_bf16_f32 v198, v82, v84
	v_add_f32_e32 v85, v86, v88
	s_waitcnt lgkmcnt(2)
	v_mfma_f32_32x32x16_bf16 v[114:129], v[70:73], v[150:153], v[114:129]
	v_cvt_pk_bf16_f32 v199, v86, v88
	v_sub_f32_e32 v70, v78, v230
	v_exp_f32_e32 v82, v70
	v_sub_f32_e32 v70, v79, v230
	s_waitcnt lgkmcnt(1)
; #define LAS __attribute__((address_space(3)))
; __device__ __forceinline__ unsigned cvt_pk(float lo, float hi) { unsigned r; asm volatile("v_cvt_pk_bf16_f32 %0, %1, %2" : "=v"(r) : "v"(lo), "v"(hi)); return r; }
; __device__ __forceinline__ void attn_unit(LAS unsigned char* lds, int b, int h, int q0, int kbeg, int ntiles, const bf16_t* Q, const bf16_t* K, const bf16_t* Vt, bf16_t* cat) {
;     ...
;         for (int ds = 0; ds < 12; ++ds) {
;             bf16x8 na = ka, nb = kbb;
;             if (ds < 11) { na = *(const LAS bf16x8*)(kb + (ds + 1) * 32); nb = *(const LAS bf16x8*)(kb + 32 * (KP * 2) + (ds + 1) * 32); }
;             pn0 = __builtin_amdgcn_mfma_f32_32x32x16_bf16(ka, qf[ds], pn0, 0, 0, 0);
;             pn1 = __builtin_amdgcn_mfma_f32_32x32x16_bf16(kbb, qf[ds], pn1, 0, 0, 0);
;             if (ds < 8) {
;                 float e[4];
; #pragma unroll
;                 for (int j = 0; j < 4; ++j) { const float v = ds < 4 ? pc0[4 * ds + j] : pc1[4 * (ds - 4) + j]; e[j] = __builtin_amdgcn_exp2f(v - mrun); }
;                 ps += (e[0] + e[1]) + (e[2] + e[3]);
;                 const unsigned w0 = cvt_pk(e[0], e[1]), w1 = cvt_pk(e[2], e[3]);
;                 if ((ds & 1) == 0) { pw[ds >> 1].x = w0; pw[ds >> 1].y = w1; } else { pw[ds >> 1].z = w0; pw[ds >> 1].w = w1; }
;             }
;             ka = na; kbb = nb;
;             __builtin_amdgcn_sched_barrier(0);
;         }
;         lrun += ps;
;         const LAS unsigned char* vb = lds + 2 * AK_BYTES + buf * AV_BYTES + r32 * AV_PITCH + hi * 8;
; #pragma unroll
;         for (int d = 0; d < 4; ++d)
; #pragma unroll
;             for (int ks = 0; ks < 4; ++ks) {
;                 const s16x4 lo = *(const LAS s16x4*)(vb + d * 32 * AV_PITCH + ks * 32), hh = *(const LAS s16x4*)(vb + d * 32 * AV_PITCH + ks * 32 + 16);
;                 const bf16x8 vf = (bf16x8){lo[0], lo[1], lo[2], lo[3], hh[0], hh[1], hh[2], hh[3]};
;                 o[d] = __builtin_amdgcn_mfma_f32_32x32x16_bf16(vf, __builtin_bit_cast(bf16x8, pw[ks]), o[d], 0, 0, 0);
;             }
;         { float mx = fmaxf(pn0[0], pn1[0]);
; #pragma unroll
;           for (int r = 1; r < 16; ++r) mx = fmaxf(mx, fmaxf(pn0[r], pn1[r]));
;           mxc = fmaxf(mx, __shfl_xor(mx, 32)); }
;         if (kt + 1 < ntiles) ASTOREV(buf ^ 1);
;         asm volatile("s_waitcnt vmcnt(0)" ::: "memory");
;         __syncthreads();
	v_mfma_f32_32x32x16_bf16 v[98:113], v[66:69], v[146:149], v[98:113]
	v_exp_f32_e32 v84, v70
	v_sub_f32_e32 v70, v80, v230
	v_sub_f32_e32 v66, v81, v230
	v_exp_f32_e32 v92, v70
	v_exp_f32_e32 v86, v66
	ds_read_b128 v[66:69], v236 offset:256
	ds_read_b128 v[70:73], v236 offset:13056
	v_add_f32_e32 v78, v82, v84
	v_add_f32_e32 v79, v83, v85
	s_waitcnt lgkmcnt(2)
	v_mfma_f32_32x32x16_bf16 v[114:129], v[74:77], v[146:149], v[114:129]
	v_add_f32_e64 v80, v92, v86
	v_add_f32_e64 v81, v93, v87
	v_cvt_pk_bf16_f32 v200, v82, v84
	v_cvt_pk_bf16_f32 v201, v92, v86
	v_add_f32_e64 v78, v78, v80
	v_add_f32_e64 v79, v79, v81
	v_add_f32_e32 v237, v78, v79
	s_waitcnt lgkmcnt(1)
	v_mfma_f32_32x32x16_bf16 v[98:113], v[66:69], v[142:145], v[98:113]
	ds_read_b128 v[66:69], v236 offset:288
	ds_read_b128 v[74:77], v236 offset:13088
	s_waitcnt lgkmcnt(2)
	v_mfma_f32_32x32x16_bf16 v[114:129], v[70:73], v[142:145], v[114:129]
	s_waitcnt lgkmcnt(1)
	v_mfma_f32_32x32x16_bf16 v[98:113], v[66:69], v[138:141], v[98:113]
	ds_read_b128 v[66:69], v236 offset:320
	ds_read_b128 v[70:73], v236 offset:13120
	s_waitcnt lgkmcnt(2)
	v_mfma_f32_32x32x16_bf16 v[114:129], v[74:77], v[138:141], v[114:129]
	s_waitcnt lgkmcnt(1)
	v_mfma_f32_32x32x16_bf16 v[98:113], v[66:69], v[134:137], v[98:113]
	ds_read_b128 v[66:69], v236 offset:352
	ds_read_b128 v[232:235], v236 offset:13152
	s_waitcnt lgkmcnt(2)
	v_mfma_f32_32x32x16_bf16 v[114:129], v[70:73], v[134:137], v[114:129]
	s_waitcnt lgkmcnt(1)
	v_mfma_f32_32x32x16_bf16 v[82:97], v[66:69], v[130:133], v[98:113]
	s_waitcnt lgkmcnt(0)
	v_mfma_f32_32x32x16_bf16 v[66:81], v[232:235], v[130:133], v[114:129]
	s_mulk_i32 s5, 0x4400
	v_add_u32_e32 v232, s5, v229
	v_add_u32_e32 v250, 0xc800, v232
	v_add_u32_e32 v251, 0xd800, v232
	v_add_u32_e32 v252, 0xe800, v232
	v_add_u32_e32 v253, 0xf800, v232
	s_mulk_i32 s6, 0x4400
	ds_read2_b64 v[98:101], v250 offset1:2
	ds_read2_b64 v[102:105], v251 offset0:32 offset1:34
	ds_read2_b64 v[106:109], v252 offset0:64 offset1:66
	ds_read2_b64 v[110:113], v253 offset0:96 offset1:98
	ds_read2_b64 v[114:117], v250 offset0:4 offset1:6
	ds_read2_b64 v[118:121], v251 offset0:36 offset1:38
	ds_read2_b64 v[122:125], v252 offset0:68 offset1:70
	ds_read2_b64 v[126:129], v253 offset0:100 offset1:102
	v_add_f32_e32 v202, v202, v237
	v_max3_f32 v254, v82, v66, v83
	v_max3_f32 v254, v254, v67, v84
	v_max3_f32 v254, v254, v68, v85
	v_max3_f32 v254, v254, v69, v86
	s_waitcnt lgkmcnt(7)
	v_mfma_f32_32x32x16_bf16 v[50:65], v[98:101], v[186:189], v[50:65]
	ds_read2_b64 v[98:101], v250 offset0:8 offset1:10
	v_max3_f32 v254, v254, v70, v87
	v_max3_f32 v254, v254, v71, v88
	s_waitcnt lgkmcnt(7)
	v_mfma_f32_32x32x16_bf16 v[34:49], v[102:105], v[186:189], v[34:49]
	ds_read2_b64 v[102:105], v251 offset0:40 offset1:42
	v_max3_f32 v254, v254, v72, v89
	v_max3_f32 v254, v254, v73, v90
	s_waitcnt lgkmcnt(7)
	v_mfma_f32_32x32x16_bf16 v[18:33], v[106:109], v[186:189], v[18:33]
	ds_read2_b64 v[106:109], v252 offset0:72 offset1:74
	v_max3_f32 v254, v254, v74, v91
	v_max3_f32 v254, v254, v75, v92
	s_waitcnt lgkmcnt(7)
	v_mfma_f32_32x32x16_bf16 v[2:17], v[110:113], v[186:189], v[2:17]
	ds_read2_b64 v[110:113], v253 offset0:104 offset1:106
	v_max3_f32 v254, v254, v76, v93
	v_max3_f32 v254, v254, v77, v94
	s_waitcnt lgkmcnt(7)
	v_mfma_f32_32x32x16_bf16 v[50:65], v[114:117], v[190:193], v[50:65]
	ds_read2_b64 v[114:117], v250 offset0:12 offset1:14
	v_max3_f32 v254, v254, v78, v95
	v_max3_f32 v254, v254, v79, v96
	s_waitcnt lgkmcnt(7)
	v_mfma_f32_32x32x16_bf16 v[34:49], v[118:121], v[190:193], v[34:49]
	ds_read2_b64 v[118:121], v251 offset0:44 offset1:46
	v_max3_f32 v254, v254, v80, v97
	v_max_f32_e32 v254, v254, v81
	s_waitcnt lgkmcnt(7)
	v_mfma_f32_32x32x16_bf16 v[18:33], v[122:125], v[190:193], v[18:33]
	ds_read2_b64 v[122:125], v252 offset0:76 offset1:78
	v_lshl_add_u64 v[212:213], v[212:213], 0, s[60:61]
	v_lshl_add_u64 v[214:215], v[214:215], 0, s[60:61]
	s_waitcnt lgkmcnt(7)
	v_mfma_f32_32x32x16_bf16 v[2:17], v[126:129], v[190:193], v[2:17]
	ds_read2_b64 v[126:129], v253 offset0:108 offset1:110
	v_lshl_add_u64 v[216:217], v[216:217], 0, s[60:61]
	v_lshl_add_u64 v[218:219], v[218:219], 0, s[60:61]
	v_lshl_add_u64 v[220:221], v[220:221], 0, s[66:67]
	ds_bpermute_b32 v255, v207, v254
	s_waitcnt lgkmcnt(8)
	v_mfma_f32_32x32x16_bf16 v[50:65], v[98:101], v[194:197], v[50:65]
	s_waitcnt lgkmcnt(7)
	v_mfma_f32_32x32x16_bf16 v[34:49], v[102:105], v[194:197], v[34:49]
	s_waitcnt lgkmcnt(6)
	v_mfma_f32_32x32x16_bf16 v[18:33], v[106:109], v[194:197], v[18:33]
	s_waitcnt lgkmcnt(5)
	v_mfma_f32_32x32x16_bf16 v[2:17], v[110:113], v[194:197], v[2:17]
	s_waitcnt lgkmcnt(0)
	v_max_f32_e32 v255, v255, v255
	v_max_f32_e32 v98, v254, v255
	v_add_u32_e32 v255, s6, v231
	v_add_u32_e32 v238, 0xc800, v255
	v_add_u32_e32 v255, 0xea00, v255
	s_cmp_lg_u32 s4, 34
	s_waitcnt vmcnt(0)
	ds_write2_b64 v238, v[178:179], v[180:181] offset1:1
	ds_write2_b64 v255, v[182:183], v[184:185] offset1:1
	s_waitcnt vmcnt(0)
	s_waitcnt lgkmcnt(0)
	s_barrier
	v_mfma_f32_32x32x16_bf16 v[50:65], v[114:117], v[198:201], v[50:65]
	v_mfma_f32_32x32x16_bf16 v[34:49], v[118:121], v[198:201], v[34:49]
	v_mfma_f32_32x32x16_bf16 v[18:33], v[122:125], v[198:201], v[18:33]
	v_mfma_f32_32x32x16_bf16 v[2:17], v[126:129], v[198:201], v[2:17]
	s_cbranch_scc0 .LBB0_819

; #define LAS __attribute__((address_space(3)))
; __device__ __forceinline__ unsigned cvt_pk(float lo, float hi) { unsigned r; asm volatile("v_cvt_pk_bf16_f32 %0, %1, %2" : "=v"(r) : "v"(lo), "v"(hi)); return r; }
; __device__ __forceinline__ void attn_unit(LAS unsigned char* lds, int b, int h, int q0, int kbeg, int ntiles, const bf16_t* Q, const bf16_t* K, const bf16_t* Vt, bf16_t* cat) {
;     ...
;         const LAS unsigned char* kb = lds + (buf ^ 1) * AK_BYTES + r32 * (KP * 2) + hi * 16;
;         f32x16 pn0, pn1;
; #pragma unroll
;         for (int r = 0; r < 16; ++r) { pn0[r] = 0.f; pn1[r] = 0.f; }
;         float ps = 0.f; u32x4 pw[4];
;         bf16x8 ka = *(const LAS bf16x8*)(kb), kbb = *(const LAS bf16x8*)(kb + 32 * (KP * 2));
; #pragma unroll
;         for (int ds = 0; ds < 12; ++ds) {
;             bf16x8 na = ka, nb = kbb;
;             if (ds < 11) { na = *(const LAS bf16x8*)(kb + (ds + 1) * 32); nb = *(const LAS bf16x8*)(kb + 32 * (KP * 2) + (ds + 1) * 32); }
;             pn0 = __builtin_amdgcn_mfma_f32_32x32x16_bf16(ka, qf[ds], pn0, 0, 0, 0);
;             pn1 = __builtin_amdgcn_mfma_f32_32x32x16_bf16(kbb, qf[ds], pn1, 0, 0, 0);
;             if (ds < 8) {
;                 float e[4];
; #pragma unroll
;                 for (int j = 0; j < 4; ++j) { const float v = ds < 4 ? pc0[4 * ds + j] : pc1[4 * (ds - 4) + j]; e[j] = __builtin_amdgcn_exp2f(v - mrun); }
;                 ps += (e[0] + e[1]) + (e[2] + e[3]);
;                 const unsigned w0 = cvt_pk(e[0], e[1]), w1 = cvt_pk(e[2], e[3]);
;                 if ((ds & 1) == 0) { pw[ds >> 1].x = w0; pw[ds >> 1].y = w1; } else { pw[ds >> 1].z = w0; pw[ds >> 1].w = w1; }
;             }
;             ka = na; kbb = nb;
;             __builtin_amdgcn_sched_barrier(0);
;         }
.LBB0_1840:
	s_xor_b32 s6, s5, 1
	s_mul_i32 s7, s6, 0x6400
	v_add_u32_e32 v233, s7, v229
	ds_read_b128 v[98:101], v233
	v_sub_f32_e32 v82, v82, v231
	v_exp_f32_e32 v197, v82
	v_sub_f32_e32 v82, v84, v231
	v_exp_f32_e32 v201, v82
	v_sub_f32_e32 v82, v85, v231
	v_exp_f32_e32 v235, v82
	v_sub_f32_e32 v82, v86, v231
	v_exp_f32_e32 v196, v82
	v_sub_f32_e32 v82, v87, v231
	s_waitcnt lgkmcnt(0)
	v_mfma_f32_32x32x16_bf16 v[98:113], v[98:101], v[174:177], 0
	v_exp_f32_e32 v198, v82
	v_sub_f32_e32 v82, v88, v231
	v_sub_f32_e32 v83, v83, v231
	v_exp_f32_e32 v200, v82
	v_sub_f32_e32 v82, v89, v231
	v_exp_f32_e32 v199, v83
	v_exp_f32_e32 v234, v82
	ds_read_b128 v[188:191], v233 offset:32
	ds_read_b128 v[114:117], v233 offset:12800
	ds_read_b128 v[192:195], v233 offset:12832
	s_add_i32 s4, s4, 1
	v_add_f32_e32 v82, v196, v198
	v_add_f32_e32 v83, v197, v199
	v_add_f32_e32 v84, v200, v234
	v_add_f32_e32 v85, v201, v235
	s_waitcnt lgkmcnt(1)
	v_mfma_f32_32x32x16_bf16 v[114:129], v[114:117], v[174:177], 0
	v_add_f32_e64 v236, v82, v84
	v_add_f32_e64 v237, v83, v85
	v_cvt_pk_bf16_f32 v186, v197, v199
	v_cvt_pk_bf16_f32 v187, v201, v235
	v_add_f32_e32 v237, 0, v237
	v_mfma_f32_32x32x16_bf16 v[98:113], v[188:191], v[170:173], v[98:113]
	ds_read_b128 v[82:85], v233 offset:64
	ds_read_b128 v[86:89], v233 offset:12864
	v_add_f32_e32 v197, v236, v237
	v_cvt_pk_bf16_f32 v188, v196, v198
	v_cvt_pk_bf16_f32 v189, v200, v234
	s_waitcnt lgkmcnt(2)
	v_mfma_f32_32x32x16_bf16 v[114:129], v[192:195], v[170:173], v[114:129]
	v_sub_f32_e32 v90, v90, v231
	s_waitcnt lgkmcnt(1)
	v_mfma_f32_32x32x16_bf16 v[98:113], v[82:85], v[166:169], v[98:113]
	v_exp_f32_e32 v190, v90
	v_sub_f32_e32 v90, v91, v231
	v_exp_f32_e32 v192, v90
	v_sub_f32_e32 v90, v92, v231
	v_sub_f32_e32 v82, v93, v231
	v_exp_f32_e32 v191, v90
	v_exp_f32_e32 v193, v82
	ds_read_b128 v[82:85], v233 offset:96
	ds_read_b128 v[90:93], v233 offset:12896
	s_waitcnt lgkmcnt(2)
	v_mfma_f32_32x32x16_bf16 v[114:129], v[86:89], v[166:169], v[114:129]
	v_add_f32_e64 v194, v190, v192
	v_add_f32_e64 v195, v191, v193
	v_add_f32_e64 v198, v194, v194
	v_add_f32_e64 v199, v194, v195
	v_cvt_pk_bf16_f32 v190, v190, v192
	v_cvt_pk_bf16_f32 v191, v191, v193
	v_sub_f32_e32 v86, v94, v231
	s_waitcnt lgkmcnt(1)
	v_mfma_f32_32x32x16_bf16 v[98:113], v[82:85], v[162:165], v[98:113]
	v_exp_f32_e32 v94, v86
	v_sub_f32_e32 v86, v95, v231
	v_exp_f32_e32 v192, v86
	v_sub_f32_e32 v86, v96, v231
	v_sub_f32_e32 v82, v97, v231
	v_exp_f32_e32 v96, v86
	v_exp_f32_e32 v193, v82
	ds_read_b128 v[82:85], v233 offset:128
	ds_read_b128 v[86:89], v233 offset:12928
	v_add_f32_e32 v95, v94, v192
	v_cvt_pk_bf16_f32 v192, v94, v192
	v_add_f32_e32 v97, v96, v193
	s_waitcnt lgkmcnt(2)
	v_mfma_f32_32x32x16_bf16 v[114:129], v[90:93], v[162:165], v[114:129]
	v_cvt_pk_bf16_f32 v193, v96, v193
	v_sub_f32_e32 v66, v66, v231
	v_exp_f32_e32 v94, v66
	v_sub_f32_e32 v66, v67, v231
	v_exp_f32_e32 v96, v66
	v_sub_f32_e32 v66, v68, v231
	v_exp_f32_e32 v198, v66
	s_waitcnt lgkmcnt(1)
	v_mfma_f32_32x32x16_bf16 v[98:113], v[82:85], v[158:161], v[98:113]
	v_sub_f32_e32 v66, v69, v231
	v_exp_f32_e32 v196, v66
	ds_read_b128 v[66:69], v233 offset:160
	ds_read_b128 v[82:85], v233 offset:12960
	v_add_f32_e32 v90, v94, v96
	v_add_f32_e32 v91, v95, v97
	v_cvt_pk_bf16_f32 v194, v94, v96
	v_add_f32_e32 v92, v198, v196
	v_add_f32_e32 v93, v199, v197
	v_cvt_pk_bf16_f32 v195, v198, v196
	s_waitcnt lgkmcnt(2)
	v_mfma_f32_32x32x16_bf16 v[114:129], v[86:89], v[158:161], v[114:129]
	v_add_f32_e64 v90, v90, v92
	v_add_f32_e64 v91, v91, v93
	v_add_f32_e64 v86, v90, v90
	v_add_f32_e64 v87, v90, v91
	v_sub_f32_e32 v70, v70, v231
	v_exp_f32_e32 v88, v70
	v_sub_f32_e32 v70, v71, v231
	s_waitcnt lgkmcnt(1)
	v_mfma_f32_32x32x16_bf16 v[98:113], v[66:69], v[154:157], v[98:113]
	v_exp_f32_e32 v90, v70
	v_sub_f32_e32 v70, v72, v231
	v_sub_f32_e32 v66, v73, v231
	v_exp_f32_e32 v89, v70
	v_exp_f32_e32 v91, v66
	ds_read_b128 v[66:69], v233 offset:192
	ds_read_b128 v[70:73], v233 offset:12992
	v_cvt_pk_bf16_f32 v196, v88, v90
	s_waitcnt lgkmcnt(2)
	v_mfma_f32_32x32x16_bf16 v[114:129], v[82:85], v[154:157], v[114:129]
	v_add_f32_e64 v92, v88, v90
	v_add_f32_e64 v93, v89, v91
	v_cvt_pk_bf16_f32 v197, v89, v91
	v_add_f32_e32 v93, v92, v93
	v_add_f32_e32 v92, v92, v92
	v_sub_f32_e32 v74, v74, v231
	s_waitcnt lgkmcnt(1)
	v_mfma_f32_32x32x16_bf16 v[98:113], v[66:69], v[150:153], v[98:113]
	v_exp_f32_e32 v82, v74
	v_sub_f32_e32 v74, v75, v231
	v_exp_f32_e32 v84, v74
	v_sub_f32_e32 v74, v76, v231
	v_sub_f32_e32 v66, v77, v231
	v_exp_f32_e32 v86, v74
	v_exp_f32_e32 v88, v66
	ds_read_b128 v[66:69], v233 offset:224
	ds_read_b128 v[74:77], v233 offset:13024
	v_add_f32_e32 v83, v82, v84
	v_cvt_pk_bf16_f32 v198, v82, v84
	v_add_f32_e32 v85, v86, v88
	s_waitcnt lgkmcnt(2)
	v_mfma_f32_32x32x16_bf16 v[114:129], v[70:73], v[150:153], v[114:129]
	v_cvt_pk_bf16_f32 v199, v86, v88
	v_sub_f32_e32 v70, v78, v231
	v_exp_f32_e32 v82, v70
	v_sub_f32_e32 v70, v79, v231
	s_waitcnt lgkmcnt(1)
; #define LAS __attribute__((address_space(3)))
; __device__ __forceinline__ unsigned cvt_pk(float lo, float hi) { unsigned r; asm volatile("v_cvt_pk_bf16_f32 %0, %1, %2" : "=v"(r) : "v"(lo), "v"(hi)); return r; }
; __device__ __forceinline__ void attn_unit(LAS unsigned char* lds, int b, int h, int q0, int kbeg, int ntiles, const bf16_t* Q, const bf16_t* K, const bf16_t* Vt, bf16_t* cat) {
;     ...
;         for (int ds = 0; ds < 12; ++ds) {
;             bf16x8 na = ka, nb = kbb;
;             if (ds < 11) { na = *(const LAS bf16x8*)(kb + (ds + 1) * 32); nb = *(const LAS bf16x8*)(kb + 32 * (KP * 2) + (ds + 1) * 32); }
;             pn0 = __builtin_amdgcn_mfma_f32_32x32x16_bf16(ka, qf[ds], pn0, 0, 0, 0);
;             pn1 = __builtin_amdgcn_mfma_f32_32x32x16_bf16(kbb, qf[ds], pn1, 0, 0, 0);
;             if (ds < 8) {
;                 float e[4];
; #pragma unroll
;                 for (int j = 0; j < 4; ++j) { const float v = ds < 4 ? pc0[4 * ds + j] : pc1[4 * (ds - 4) + j]; e[j] = __builtin_amdgcn_exp2f(v - mrun); }
;                 ps += (e[0] + e[1]) + (e[2] + e[3]);
;                 const unsigned w0 = cvt_pk(e[0], e[1]), w1 = cvt_pk(e[2], e[3]);
;                 if ((ds & 1) == 0) { pw[ds >> 1].x = w0; pw[ds >> 1].y = w1; } else { pw[ds >> 1].z = w0; pw[ds >> 1].w = w1; }
;             }
;             ka = na; kbb = nb;
;             __builtin_amdgcn_sched_barrier(0);
;         }
;         lrun += ps;
;         const LAS unsigned char* vb = lds + 2 * AK_BYTES + buf * AV_BYTES + r32 * AV_PITCH + hi * 8;
; #pragma unroll
;         for (int d = 0; d < 4; ++d)
; #pragma unroll
;             for (int ks = 0; ks < 4; ++ks) {
;                 const s16x4 lo = *(const LAS s16x4*)(vb + d * 32 * AV_PITCH + ks * 32), hh = *(const LAS s16x4*)(vb + d * 32 * AV_PITCH + ks * 32 + 16);
;                 const bf16x8 vf = (bf16x8){lo[0], lo[1], lo[2], lo[3], hh[0], hh[1], hh[2], hh[3]};
;                 o[d] = __builtin_amdgcn_mfma_f32_32x32x16_bf16(vf, __builtin_bit_cast(bf16x8, pw[ks]), o[d], 0, 0, 0);
;             }
;         { float mx = fmaxf(pn0[0], pn1[0]);
; #pragma unroll
;           for (int r = 1; r < 16; ++r) mx = fmaxf(mx, fmaxf(pn0[r], pn1[r]));
;           mxc = fmaxf(mx, __shfl_xor(mx, 32)); }
;         if (kt + 1 < ntiles) ASTOREV(buf ^ 1);
;         asm volatile("s_waitcnt vmcnt(0)" ::: "memory");
;         __syncthreads();
	v_mfma_f32_32x32x16_bf16 v[98:113], v[66:69], v[146:149], v[98:113]
	v_exp_f32_e32 v84, v70
	v_sub_f32_e32 v70, v80, v231
	v_sub_f32_e32 v66, v81, v231
	v_exp_f32_e32 v92, v70
	v_exp_f32_e32 v86, v66
	ds_read_b128 v[66:69], v233 offset:256
	ds_read_b128 v[70:73], v233 offset:13056
	v_add_f32_e32 v78, v82, v84
	v_add_f32_e32 v79, v83, v85
	s_waitcnt lgkmcnt(2)
	v_mfma_f32_32x32x16_bf16 v[114:129], v[74:77], v[146:149], v[114:129]
	v_add_f32_e64 v80, v92, v86
	v_add_f32_e64 v81, v93, v87
	v_cvt_pk_bf16_f32 v200, v82, v84
	v_cvt_pk_bf16_f32 v201, v92, v86
	v_add_f32_e64 v78, v78, v80
	v_add_f32_e64 v79, v79, v81
	v_add_f32_e32 v238, v78, v79
	s_waitcnt lgkmcnt(1)
	v_mfma_f32_32x32x16_bf16 v[98:113], v[66:69], v[142:145], v[98:113]
	ds_read_b128 v[66:69], v233 offset:288
	ds_read_b128 v[74:77], v233 offset:13088
	s_waitcnt lgkmcnt(2)
	v_mfma_f32_32x32x16_bf16 v[114:129], v[70:73], v[142:145], v[114:129]
	s_waitcnt lgkmcnt(1)
	v_mfma_f32_32x32x16_bf16 v[98:113], v[66:69], v[138:141], v[98:113]
	ds_read_b128 v[66:69], v233 offset:320
	ds_read_b128 v[70:73], v233 offset:13120
	s_waitcnt lgkmcnt(2)
	v_mfma_f32_32x32x16_bf16 v[114:129], v[74:77], v[138:141], v[114:129]
	s_waitcnt lgkmcnt(1)
	v_mfma_f32_32x32x16_bf16 v[98:113], v[66:69], v[134:137], v[98:113]
	ds_read_b128 v[66:69], v233 offset:352
	ds_read_b128 v[234:237], v233 offset:13152
	s_waitcnt lgkmcnt(2)
	v_mfma_f32_32x32x16_bf16 v[114:129], v[70:73], v[134:137], v[114:129]
	s_waitcnt lgkmcnt(1)
	v_mfma_f32_32x32x16_bf16 v[82:97], v[66:69], v[130:133], v[98:113]
	s_waitcnt lgkmcnt(0)
	v_mfma_f32_32x32x16_bf16 v[66:81], v[234:237], v[130:133], v[114:129]
	s_mulk_i32 s5, 0x4400
	v_add_u32_e32 v233, s5, v230
	v_add_u32_e32 v250, 0xc800, v233
	v_add_u32_e32 v251, 0xd800, v233
	v_add_u32_e32 v252, 0xe800, v233
	v_add_u32_e32 v253, 0xf800, v233
	s_mulk_i32 s6, 0x4400
	ds_read2_b64 v[98:101], v250 offset1:2
	ds_read2_b64 v[102:105], v251 offset0:32 offset1:34
	ds_read2_b64 v[106:109], v252 offset0:64 offset1:66
	ds_read2_b64 v[110:113], v253 offset0:96 offset1:98
	ds_read2_b64 v[114:117], v250 offset0:4 offset1:6
	ds_read2_b64 v[118:121], v251 offset0:36 offset1:38
	ds_read2_b64 v[122:125], v252 offset0:68 offset1:70
	ds_read2_b64 v[126:129], v253 offset0:100 offset1:102
	v_add_f32_e32 v202, v202, v238
	v_max3_f32 v254, v82, v66, v83
	v_max3_f32 v254, v254, v67, v84
	v_max3_f32 v254, v254, v68, v85
	v_max3_f32 v254, v254, v69, v86
	s_waitcnt lgkmcnt(7)
	v_mfma_f32_32x32x16_bf16 v[50:65], v[98:101], v[186:189], v[50:65]
	ds_read2_b64 v[98:101], v250 offset0:8 offset1:10
	v_max3_f32 v254, v254, v70, v87
	v_max3_f32 v254, v254, v71, v88
	s_waitcnt lgkmcnt(7)
	v_mfma_f32_32x32x16_bf16 v[34:49], v[102:105], v[186:189], v[34:49]
	ds_read2_b64 v[102:105], v251 offset0:40 offset1:42
	v_max3_f32 v254, v254, v72, v89
	v_max3_f32 v254, v254, v73, v90
	s_waitcnt lgkmcnt(7)
	v_mfma_f32_32x32x16_bf16 v[18:33], v[106:109], v[186:189], v[18:33]
	ds_read2_b64 v[106:109], v252 offset0:72 offset1:74
	v_max3_f32 v254, v254, v74, v91
	v_max3_f32 v254, v254, v75, v92
	s_waitcnt lgkmcnt(7)
	v_mfma_f32_32x32x16_bf16 v[2:17], v[110:113], v[186:189], v[2:17]
	ds_read2_b64 v[110:113], v253 offset0:104 offset1:106
	v_max3_f32 v254, v254, v76, v93
	v_max3_f32 v254, v254, v77, v94
	s_waitcnt lgkmcnt(7)
	v_mfma_f32_32x32x16_bf16 v[50:65], v[114:117], v[190:193], v[50:65]
	ds_read2_b64 v[114:117], v250 offset0:12 offset1:14
	v_max3_f32 v254, v254, v78, v95
	v_max3_f32 v254, v254, v79, v96
	s_waitcnt lgkmcnt(7)
	v_mfma_f32_32x32x16_bf16 v[34:49], v[118:121], v[190:193], v[34:49]
	ds_read2_b64 v[118:121], v251 offset0:44 offset1:46
	v_max3_f32 v254, v254, v80, v97
	v_max_f32_e32 v254, v254, v81
	s_waitcnt lgkmcnt(7)
	v_mfma_f32_32x32x16_bf16 v[18:33], v[122:125], v[190:193], v[18:33]
	ds_read2_b64 v[122:125], v252 offset0:76 offset1:78
	v_lshl_add_u64 v[214:215], v[214:215], 0, s[38:39]
	v_lshl_add_u64 v[216:217], v[216:217], 0, s[38:39]
	s_waitcnt lgkmcnt(7)
	v_mfma_f32_32x32x16_bf16 v[2:17], v[126:129], v[190:193], v[2:17]
	ds_read2_b64 v[126:129], v253 offset0:108 offset1:110
	v_lshl_add_u64 v[218:219], v[218:219], 0, s[38:39]
	v_lshl_add_u64 v[220:221], v[220:221], 0, s[38:39]
	v_lshl_add_u64 v[222:223], v[222:223], 0, s[40:41]
	ds_bpermute_b32 v255, v209, v254
	s_waitcnt lgkmcnt(8)
	v_mfma_f32_32x32x16_bf16 v[50:65], v[98:101], v[194:197], v[50:65]
	s_waitcnt lgkmcnt(7)
	v_mfma_f32_32x32x16_bf16 v[34:49], v[102:105], v[194:197], v[34:49]
	s_waitcnt lgkmcnt(6)
	v_mfma_f32_32x32x16_bf16 v[18:33], v[106:109], v[194:197], v[18:33]
	s_waitcnt lgkmcnt(5)
	v_mfma_f32_32x32x16_bf16 v[2:17], v[110:113], v[194:197], v[2:17]
	s_waitcnt lgkmcnt(0)
	v_max_f32_e32 v255, v255, v255
	v_max_f32_e32 v98, v254, v255
	v_add_u32_e32 v255, s6, v232
	v_add_u32_e32 v239, 0xc800, v255
	v_add_u32_e32 v255, 0xea00, v255
	s_cmp_lg_u32 s4, 34
	s_waitcnt vmcnt(0)
	ds_write2_b64 v239, v[178:179], v[180:181] offset1:1
	ds_write2_b64 v255, v[182:183], v[184:185] offset1:1
	s_waitcnt vmcnt(0)
	s_waitcnt lgkmcnt(0)
	s_barrier
	v_mfma_f32_32x32x16_bf16 v[50:65], v[114:117], v[198:201], v[50:65]
	v_mfma_f32_32x32x16_bf16 v[34:49], v[118:121], v[198:201], v[34:49]
	v_mfma_f32_32x32x16_bf16 v[18:33], v[122:125], v[198:201], v[18:33]
	v_mfma_f32_32x32x16_bf16 v[2:17], v[126:129], v[198:201], v[2:17]
	s_cbranch_scc0 .LBB0_1845
